# topbar + early L2 write-back: local arrivers with 8 resp. 2 arrivals missing start buffer_wbl2 while waiting
# baseline (speedup 1.0000x reference)
.LBB0_127:
	s_or_b64 exec, exec, s[20:21]
	v_cvt_f32_u32_e32 v5, v3
	s_waitcnt vmcnt(0)
	v_readfirstlane_b32 s3, v4
	v_sub_u32_e32 v4, 0, v3
	v_rcp_iflag_f32_e32 v5, v5
	v_add_u32_e32 v6, s3, v2
	v_mul_f32_e32 v5, 0x4f7ffffe, v5
	v_cvt_u32_f32_e32 v5, v5
	v_mul_lo_u32 v2, v4, v5
	v_mul_hi_u32 v2, v5, v2
	v_add_u32_e32 v2, v5, v2
	v_mul_hi_u32 v2, v6, v2
	v_mul_lo_u32 v4, v2, v3
	v_sub_u32_e32 v4, v6, v4
	v_add_u32_e32 v5, 1, v2
	v_cmp_ge_u32_e32 vcc, v4, v3
	s_nop 1
	v_cndmask_b32_e32 v2, v2, v5, vcc
	v_sub_u32_e32 v5, v4, v3
	v_cndmask_b32_e32 v4, v4, v5, vcc
	v_add_u32_e32 v5, 1, v2
	v_cmp_ge_u32_e32 vcc, v4, v3
	v_add_u32_e32 v4, 1, v6
	s_nop 0
	v_cndmask_b32_e32 v2, v2, v5, vcc
	v_mul_lo_u32 v5, v3, v2
	v_add_u32_e32 v3, v5, v3
	v_cmp_ne_u32_e32 vcc, v4, v3
	s_and_saveexec_b64 s[4:5], vcc
	s_xor_b64 s[20:21], exec, s[4:5]
	s_cbranch_execz .LBB0_141
	s_waitcnt lgkmcnt(0)
	v_sub_u32_e32 v5, v3, v4
	v_cmp_eq_u32_e32 vcc, 2, v5
	v_cmp_eq_u32_e64 s[4:5], 8, v5
	s_or_b64 vcc, vcc, s[4:5]
	s_cbranch_vccz .Lnoflush_0
	buffer_wbl2 sc1
.Lnoflush_0:
	v_mad_u32_u24 v2, v2, v1, v1
	v_mov_b32_e32 v1, 0
	global_load_dword v3, v1, s[92:93] offset:-256 sc1
	s_waitcnt vmcnt(0)
	v_cmp_gt_u32_e32 vcc, v2, v3
	s_and_saveexec_b64 s[22:23], vcc
	s_cbranch_execz .LBB0_140
	s_mov_b32 s3, 1
	s_mov_b64 s[24:25], 0
	s_branch .LBB0_131

.LBB0_344:
	s_or_b64 exec, exec, s[20:21]
	v_cvt_f32_u32_e32 v5, v3
	s_waitcnt vmcnt(0)
	v_readfirstlane_b32 s4, v4
	v_sub_u32_e32 v4, 0, v3
	v_rcp_iflag_f32_e32 v5, v5
	v_add_u32_e32 v6, s4, v2
	v_mul_f32_e32 v5, 0x4f7ffffe, v5
	v_cvt_u32_f32_e32 v5, v5
	v_mul_lo_u32 v2, v4, v5
	v_mul_hi_u32 v2, v5, v2
	v_add_u32_e32 v2, v5, v2
	v_mul_hi_u32 v2, v6, v2
	v_mul_lo_u32 v4, v2, v3
	v_sub_u32_e32 v4, v6, v4
	v_add_u32_e32 v5, 1, v2
	v_cmp_ge_u32_e32 vcc, v4, v3
	s_nop 1
	v_cndmask_b32_e32 v2, v2, v5, vcc
	v_sub_u32_e32 v5, v4, v3
	v_cndmask_b32_e32 v4, v4, v5, vcc
	v_add_u32_e32 v5, 1, v2
	v_cmp_ge_u32_e32 vcc, v4, v3
	v_add_u32_e32 v4, 1, v6
	s_nop 0
	v_cndmask_b32_e32 v2, v2, v5, vcc
	v_mul_lo_u32 v5, v3, v2
	v_add_u32_e32 v3, v5, v3
	v_cmp_ne_u32_e32 vcc, v4, v3
	s_and_saveexec_b64 s[4:5], vcc
	s_xor_b64 s[20:21], exec, s[4:5]
	s_cbranch_execz .LBB0_358
	s_waitcnt lgkmcnt(0)
	v_sub_u32_e32 v5, v3, v4
	v_cmp_eq_u32_e32 vcc, 2, v5
	v_cmp_eq_u32_e64 s[4:5], 8, v5
	s_or_b64 vcc, vcc, s[4:5]
	s_cbranch_vccz .Lnoflush_1
	buffer_wbl2 sc1
.Lnoflush_1:
	v_mad_u32_u24 v2, v2, v1, v1
	v_mov_b32_e32 v1, 0
	global_load_dword v3, v1, s[92:93] offset:-256 sc1
	s_waitcnt vmcnt(0)
	v_cmp_gt_u32_e32 vcc, v2, v3
	s_and_saveexec_b64 s[22:23], vcc
	s_cbranch_execz .LBB0_357
	s_mov_b32 s4, 1
	s_mov_b64 s[24:25], 0
	s_branch .LBB0_348

.LBB0_614:
	s_or_b64 exec, exec, s[20:21]
	v_cvt_f32_u32_e32 v6, v4
	s_waitcnt vmcnt(0)
	v_readfirstlane_b32 s4, v5
	v_sub_u32_e32 v5, 0, v4
	v_rcp_iflag_f32_e32 v6, v6
	v_add_u32_e32 v7, s4, v3
	v_mul_f32_e32 v6, 0x4f7ffffe, v6
	v_cvt_u32_f32_e32 v6, v6
	v_mul_lo_u32 v3, v5, v6
	v_mul_hi_u32 v3, v6, v3
	v_add_u32_e32 v3, v6, v3
	v_mul_hi_u32 v3, v7, v3
	v_mul_lo_u32 v5, v3, v4
	v_sub_u32_e32 v5, v7, v5
	v_add_u32_e32 v6, 1, v3
	v_cmp_ge_u32_e32 vcc, v5, v4
	s_nop 1
	v_cndmask_b32_e32 v3, v3, v6, vcc
	v_sub_u32_e32 v6, v5, v4
	v_cndmask_b32_e32 v5, v5, v6, vcc
	v_add_u32_e32 v6, 1, v3
	v_cmp_ge_u32_e32 vcc, v5, v4
	v_add_u32_e32 v5, 1, v7
	s_nop 0
	v_cndmask_b32_e32 v3, v3, v6, vcc
	v_mul_lo_u32 v6, v4, v3
	v_add_u32_e32 v4, v6, v4
	v_cmp_ne_u32_e32 vcc, v5, v4
	s_and_saveexec_b64 s[4:5], vcc
	s_xor_b64 s[20:21], exec, s[4:5]
	s_cbranch_execz .LBB0_628
	s_waitcnt lgkmcnt(0)
	v_sub_u32_e32 v6, v4, v5
	v_cmp_eq_u32_e32 vcc, 2, v6
	v_cmp_eq_u32_e64 s[4:5], 8, v6
	s_or_b64 vcc, vcc, s[4:5]
	s_cbranch_vccz .Lnoflush_3
	buffer_wbl2 sc1
.Lnoflush_3:
	v_mad_u32_u24 v3, v3, v2, v2
	v_mov_b32_e32 v2, 0
	global_load_dword v4, v2, s[92:93] offset:-256 sc1
	s_waitcnt vmcnt(0)
	v_cmp_gt_u32_e32 vcc, v3, v4
	s_and_saveexec_b64 s[22:23], vcc
	s_cbranch_execz .LBB0_627
	s_mov_b32 s4, 1
	s_mov_b64 s[24:25], 0
	s_branch .LBB0_618

.LBB0_1559:
	s_or_b64 exec, exec, s[18:19]
	v_cvt_f32_u32_e32 v6, v4
	s_waitcnt vmcnt(0)
	v_readfirstlane_b32 s4, v5
	v_sub_u32_e32 v5, 0, v4
	v_rcp_iflag_f32_e32 v6, v6
	v_add_u32_e32 v7, s4, v3
	v_mul_f32_e32 v6, 0x4f7ffffe, v6
	v_cvt_u32_f32_e32 v6, v6
	v_mul_lo_u32 v3, v5, v6
	v_mul_hi_u32 v3, v6, v3
	v_add_u32_e32 v3, v6, v3
	v_mul_hi_u32 v3, v7, v3
	v_mul_lo_u32 v5, v3, v4
	v_sub_u32_e32 v5, v7, v5
	v_add_u32_e32 v6, 1, v3
	v_cmp_ge_u32_e32 vcc, v5, v4
	s_nop 1
	v_cndmask_b32_e32 v3, v3, v6, vcc
	v_sub_u32_e32 v6, v5, v4
	v_cndmask_b32_e32 v5, v5, v6, vcc
	v_add_u32_e32 v6, 1, v3
	v_cmp_ge_u32_e32 vcc, v5, v4
	v_add_u32_e32 v5, 1, v7
	s_nop 0
	v_cndmask_b32_e32 v3, v3, v6, vcc
	v_mul_lo_u32 v6, v4, v3
	v_add_u32_e32 v4, v6, v4
	v_cmp_ne_u32_e32 vcc, v5, v4
	s_and_saveexec_b64 s[4:5], vcc
	s_xor_b64 s[18:19], exec, s[4:5]
	s_cbranch_execz .LBB0_1573
	s_waitcnt lgkmcnt(0)
	v_sub_u32_e32 v6, v4, v5
	v_cmp_eq_u32_e32 vcc, 2, v6
	v_cmp_eq_u32_e64 s[4:5], 8, v6
	s_or_b64 vcc, vcc, s[4:5]
	s_cbranch_vccz .Lnoflush_5
	buffer_wbl2 sc1
.Lnoflush_5:
	v_mad_u32_u24 v3, v3, v2, v2
	v_mov_b32_e32 v2, 0
	global_load_dword v4, v2, s[92:93] offset:-256 sc1
	s_waitcnt vmcnt(0)
	v_cmp_gt_u32_e32 vcc, v3, v4
	s_and_saveexec_b64 s[20:21], vcc
	s_cbranch_execz .LBB0_1572
	s_mov_b32 s4, 1
	s_mov_b64 s[22:23], 0
	s_branch .LBB0_1563

.LBB0_1646:
	s_or_b64 exec, exec, s[4:5]
	v_cvt_f32_u32_e32 v5, v3
	s_waitcnt vmcnt(0)
	v_readfirstlane_b32 s4, v4
	v_sub_u32_e32 v4, 0, v3
	v_rcp_iflag_f32_e32 v5, v5
	v_add_u32_e32 v6, s4, v2
	v_mul_f32_e32 v5, 0x4f7ffffe, v5
	v_cvt_u32_f32_e32 v5, v5
	v_mul_lo_u32 v2, v4, v5
	v_mul_hi_u32 v2, v5, v2
	v_add_u32_e32 v2, v5, v2
	v_mul_hi_u32 v2, v6, v2
	v_mul_lo_u32 v4, v2, v3
	v_sub_u32_e32 v4, v6, v4
	v_add_u32_e32 v5, 1, v2
	v_cmp_ge_u32_e32 vcc, v4, v3
	s_nop 1
	v_cndmask_b32_e32 v2, v2, v5, vcc
	v_sub_u32_e32 v5, v4, v3
	v_cndmask_b32_e32 v4, v4, v5, vcc
	v_add_u32_e32 v5, 1, v2
	v_cmp_ge_u32_e32 vcc, v4, v3
	v_add_u32_e32 v4, 1, v6
	s_nop 0
	v_cndmask_b32_e32 v2, v2, v5, vcc
	v_mul_lo_u32 v5, v3, v2
	v_add_u32_e32 v3, v5, v3
	v_cmp_ne_u32_e32 vcc, v4, v3
	s_and_saveexec_b64 s[4:5], vcc
	s_xor_b64 s[4:5], exec, s[4:5]
	s_cbranch_execz .LBB0_1660
	s_waitcnt lgkmcnt(0)
	v_sub_u32_e32 v5, v3, v4
	v_cmp_eq_u32_e32 vcc, 2, v5
	v_cmp_eq_u32_e64 s[4:5], 8, v5
	s_or_b64 vcc, vcc, s[4:5]
	s_cbranch_vccz .Lnoflush_6
	buffer_wbl2 sc1
.Lnoflush_6:
	v_mad_u32_u24 v2, v2, v1, v1
	v_mov_b32_e32 v1, 0
	global_load_dword v3, v1, s[92:93] offset:-256 sc1
	s_waitcnt vmcnt(0)
	v_cmp_gt_u32_e32 vcc, v2, v3
	s_and_saveexec_b64 s[6:7], vcc
	s_cbranch_execz .LBB0_1659
	s_mov_b32 s18, 1
	s_mov_b64 s[8:9], 0
	s_branch .LBB0_1650
